# baseline (speedup 1.0000x reference)
; #define PHASE_BEGIN KArg pp = kargs(); unsigned char* ws = pp->ws; int ll = l; asm volatile("" : "+s"(ll)); (void)ws; (void)ll;
; __global__ void __launch_bounds__(NTHR, 2) mega_fwd(Params P) {
;     ...
;         for (int rep = 0; rep < REPS(8); ++rep) if (PH(8)) {
;             PHASE_BEGIN THREAD_IDS
;             unsigned* ctr = (unsigned*)(ws + WS_CTL) + 64 * (1 + ll + 2 * rep);
;             const bf16_t* Qb = B_Q; const bf16_t* KV = B_KV; const bf16_t* VT = B_VT; const bf16_t* KR = B_KR; bf16_t* OM = B_OM;
;             for (;;) {
;                 __syncthreads();
;                 if (tid == 0) lds_u[36000] = atomicAdd(ctr, 1u);
;                 __syncthreads();
;                 const int ui = (int)lds_u[36000];
;                 if (ui >= 64 + 1024) break;
.LBB0_839:
	s_or_b64 exec, exec, s[34:35]
	s_mov_b64 s[4:5], s[90:91]
	s_waitcnt lgkmcnt(0)
	s_barrier
	v_readfirstlane_b32 s100, v212
	s_cmpk_lt_u32 s100, 0x100
	s_cbranch_scc1 .Lmy_prio_skip
	s_setprio 1
.Lmy_prio_skip:
	s_load_dwordx2 s[4:5], s[4:5], 0xd0
	v_readlane_b32 s6, v247, 50
	v_mov_b32_e32 v1, v212
	s_mov_b32 s7, s2
	s_lshl_b32 s6, s6, 6
	s_ashr_i32 s7, s6, 31
	s_lshl_b64 s[6:7], s[6:7], 2
	s_waitcnt lgkmcnt(0)
	s_add_u32 s34, s4, s6
	s_addc_u32 s35, s5, s7
	s_add_u32 s48, s4, 0x1c500000
	s_addc_u32 s49, s5, 0
	s_add_u32 s38, s4, 0x10400000
	s_addc_u32 s64, s5, 0
	s_add_u32 s65, s4, 0x14500000
	s_addc_u32 s66, s5, 0
	s_add_u32 s50, s4, 0x1c000000
	s_addc_u32 s51, s5, 0
	s_add_u32 s52, s4, 0x8100000
	s_addc_u32 s53, s5, 0
	s_add_u32 s67, s4, 0x14520000
	v_cmp_eq_u32_e64 s[40:41], 0, v1
	s_addc_u32 s68, s5, 0
	s_branch .LBB0_842

; __global__ void __launch_bounds__(NTHR, 2) mega_fwd(Params P) {
;     ...
;             for (;;) {
;                 __syncthreads();
;                 if (tid == 0) lds_u[36000] = atomicAdd(ctr, 1u);
;                 __syncthreads();
;                 const int ui = (int)lds_u[36000];
;                 if (ui >= 64 + 1024) break;
;                 if (ui < 64) { const int b = ui >> 3, h = ui & 7;
;                     attn_unit(lds, Qb, KV, VT, KR, OM, MP + 64 * b, 2, h, MP + b * SKV_S, 65, 0, false);
;                 } else { const int i = ui - 64, qb = 31 - (i >> 5), bh = i & 31, b = bh >> 3, h = bh & 7;
;                     attn_unit(lds, Qb, KV, VT, KR, OM, b * SEQ + 256 * qb, 8, h, b * SEQ, 4 * qb + 4, 4 * qb, true);
;                 }
;             }
.LBB0_842:
	s_barrier
	s_and_saveexec_b64 s[42:43], s[40:41]
	s_cbranch_execz .LBB0_846
	s_mov_b64 s[46:47], exec
	s_waitcnt lgkmcnt(0)
	v_mbcnt_lo_u32_b32 v1, s46, 0
	v_mbcnt_hi_u32_b32 v1, s47, v1
	v_cmp_eq_u32_e32 vcc, 0, v1
	s_and_saveexec_b64 s[44:45], vcc
	s_cbranch_execz .LBB0_845
	s_bcnt1_i32_b64 s4, s[46:47]
	v_mov_b32_e32 v2, s4
	s_getreg_b32 s100, hwreg(HW_REG_XCC_ID, 0, 4)
	s_and_b32 s100, s100, 7
	s_lshl_b32 s101, s100, 9
	s_addk_i32 s101, 0x4800
	v_mov_b32_e32 v3, s101
	global_atomic_add v2, v3, v2, s[34:35] sc0
.LBB0_845:
	s_or_b64 exec, exec, s[44:45]
	s_waitcnt vmcnt(0)
	v_readfirstlane_b32 s4, v2
	s_cmp_lt_u32 s4, 8
	s_cbranch_scc1 .Lmy_att_samp
	s_cmpk_ge_u32 s4, 0x88
	s_cbranch_scc1 .Lmy_att_done
	s_sub_u32 s4, s4, 8
	s_and_b32 s101, s4, 31
	s_lshl_b32 s101, s101, 5
	s_lshr_b32 s4, s4, 5
	s_lshl_b32 s4, s4, 3
	s_add_u32 s4, s4, s100
	s_add_u32 s4, s4, s101
	s_add_u32 s4, s4, 64
	s_branch .Lmy_att_fin
.Lmy_att_samp:
	s_lshl_b32 s101, s100, 3
	s_add_u32 s4, s4, s101
	s_branch .Lmy_att_fin
.Lmy_att_done:
	s_movk_i32 s4, 0x440
.Lmy_att_fin:
	s_nop 1
	v_add_u32_e32 v1, s4, v1
	v_readlane_b32 s4, v247, 20
	s_nop 1
	v_mov_b32_e32 v2, s4
	ds_write_b32 v2, v1

; DI void attn_unit(unsigned char* lds, const bf16_t* Q, const bf16_t* KN, const bf16_t* VT, const bf16_t* KR, bf16_t* OM,
;                   int qrow_base, int nqw, int h, int kvbase, int ntiles, int last_base, bool prompt) {
;     ...
;             float mx = p[0][0];
; #pragma unroll
;             for (int q = 0; q < 4; ++q)
; #pragma unroll
;                 for (int i = 0; i < 16; ++i) mx = fmaxf(mx, p[q][i]);
;             mx = fmaxf(mx, __shfl_xor(mx, 32));
;             if (__any(mx > 0.f)) {
;                 const float dl = fmaxf(mx, 0.f);
;                 mrun += dl;
;                 const float alpha = __builtin_amdgcn_exp2f(-dl);
;                 lrun *= alpha;
; #pragma unroll
;                 for (int q = 0; q < 4; ++q)
; #pragma unroll
;                     for (int i = 0; i < 16; ++i) p[q][i] -= dl;
; #pragma unroll
;                 for (int i = 0; i < 16; ++i) { o0[i] *= alpha; o1[i] *= alpha; }
;             }
.LBB0_870:
	s_or_b64 exec, exec, s[62:63]
	v_max_f32_e32 v82, v67, v67
	v_max_f32_e32 v83, v66, v66
	v_max_f32_e32 v82, v83, v82
	v_max3_f32 v82, v82, v68, v69
	v_max3_f32 v82, v82, v70, v71
	v_max3_f32 v82, v82, v72, v73
	v_max3_f32 v82, v82, v74, v75
	v_max3_f32 v82, v82, v76, v77
	v_max3_f32 v82, v82, v78, v79
	v_max3_f32 v82, v82, v80, v81
	v_max3_f32 v82, v82, v34, v35
	v_max3_f32 v82, v82, v36, v37
	v_max3_f32 v82, v82, v38, v39
	v_max3_f32 v82, v82, v40, v41
	v_max3_f32 v82, v82, v42, v43
	v_max3_f32 v82, v82, v44, v45
	v_max3_f32 v82, v82, v46, v47
	v_max3_f32 v82, v82, v48, v49
	v_max3_f32 v82, v82, v50, v51
	v_max3_f32 v82, v82, v52, v53
	v_max3_f32 v82, v82, v54, v55
	v_max3_f32 v82, v82, v56, v57
	v_max3_f32 v82, v82, v58, v59
	v_max3_f32 v82, v82, v60, v61
	v_max3_f32 v82, v82, v62, v63
	v_max3_f32 v82, v82, v64, v65
	v_max3_f32 v82, v82, v174, v175
	v_max3_f32 v82, v82, v176, v177
	v_max3_f32 v82, v82, v178, v179
	v_max3_f32 v82, v82, v170, v171
	v_and_b32_e32 v84, 64, v220
	v_max3_f32 v82, v82, v164, v165
	v_xor_b32_e32 v83, 32, v220
	v_add_u32_e32 v84, 64, v84
	v_max3_f32 v82, v82, v166, v167
	v_cmp_lt_i32_e32 vcc, v83, v84
	v_max3_f32 v82, v82, v168, v169
	v_max3_f32 v82, v82, v172, v173
	v_cndmask_b32_e32 v83, v220, v83, vcc
	v_lshlrev_b32_e32 v83, 2, v83
	ds_bpermute_b32 v83, v83, v82
	s_waitcnt lgkmcnt(0)
	v_max_f32_e32 v83, v83, v83
	v_max_f32_e32 v82, v82, v83
	v_mov_b32_e32 v250, 1.0
	v_cmp_lt_f32_e32 vcc, 0, v82
	s_cbranch_vccz .LBB0_872
	v_max_f32_e32 v82, v82, v82
	v_max_f32_e32 v82, 0, v82
	v_exp_f32_e64 v250, -v82
	v_add_f32_e32 v1, v1, v82

; DI void attn_unit(unsigned char* lds, const bf16_t* Q, const bf16_t* KN, const bf16_t* VT, const bf16_t* KR, bf16_t* OM,
;                   int qrow_base, int nqw, int h, int kvbase, int ntiles, int last_base, bool prompt) {
;     ...
;                 lrun *= alpha;
; #pragma unroll
;                 for (int q = 0; q < 4; ++q)
; #pragma unroll
;                     for (int i = 0; i < 16; ++i) p[q][i] -= dl;
; #pragma unroll
;                 for (int i = 0; i < 16; ++i) { o0[i] *= alpha; o1[i] *= alpha; }
;     ...
;             float ls = 0.f;
; #pragma unroll
;             for (int q = 0; q < 4; ++q)
; #pragma unroll
;                 for (int i = 0; i < 16; ++i) { p[q][i] = __builtin_amdgcn_exp2f(p[q][i]); ls += p[q][i]; }
;             lrun += ls;
.LBB0_874:
	s_or_b64 exec, exec, s[62:63]
	v_add_f32_e32 v66, 0, v66
	v_add_f32_e32 v66, v66, v67
	v_add_f32_e32 v66, v68, v66
	v_add_f32_e32 v66, v69, v66
	v_add_f32_e32 v66, v70, v66
	v_add_f32_e32 v66, v71, v66
	v_add_f32_e32 v66, v72, v66
	v_add_f32_e32 v66, v73, v66
	v_add_f32_e32 v66, v74, v66
	v_add_f32_e32 v66, v75, v66
	v_add_f32_e32 v66, v76, v66
	v_add_f32_e32 v66, v77, v66
	v_add_f32_e32 v66, v78, v66
	v_add_f32_e32 v66, v79, v66
	v_add_f32_e32 v66, v80, v66
	v_add_f32_e32 v66, v81, v66
	v_add_f32_e32 v34, v34, v66
	v_add_f32_e32 v34, v35, v34
	v_add_f32_e32 v34, v36, v34
	v_add_f32_e32 v34, v37, v34
	v_add_f32_e32 v34, v38, v34
	v_add_f32_e32 v34, v39, v34
	v_add_f32_e32 v34, v40, v34
	v_add_f32_e32 v34, v41, v34
	v_add_f32_e32 v34, v42, v34
	v_add_f32_e32 v34, v43, v34
	v_add_f32_e32 v34, v44, v34
	v_add_f32_e32 v34, v45, v34
	v_add_f32_e32 v34, v46, v34
	v_add_f32_e32 v34, v47, v34
	v_add_f32_e32 v34, v48, v34
	v_add_f32_e32 v34, v49, v34
	v_add_f32_e32 v34, v50, v34
	v_add_f32_e32 v34, v51, v34
	v_add_f32_e32 v34, v52, v34
	v_add_f32_e32 v34, v53, v34
	v_add_f32_e32 v34, v54, v34
	v_add_f32_e32 v34, v55, v34
	v_add_f32_e32 v34, v56, v34
	v_add_f32_e32 v34, v57, v34
	v_add_f32_e32 v34, v58, v34
	v_add_f32_e32 v34, v59, v34
	v_add_f32_e32 v34, v60, v34
	v_add_f32_e32 v34, v61, v34
	v_add_f32_e32 v34, v62, v34
	v_add_f32_e32 v34, v63, v34
	v_add_f32_e32 v34, v64, v34
	v_add_f32_e32 v34, v65, v34
	v_add_f32_e32 v34, v82, v34
	v_add_f32_e32 v34, v83, v34
	v_add_f32_e32 v34, v84, v34
	v_add_f32_e32 v34, v85, v34
	v_add_f32_e32 v34, v86, v34
	v_add_f32_e32 v34, v87, v34
	v_add_f32_e32 v34, v88, v34
	v_add_f32_e32 v34, v89, v34
	v_add_f32_e32 v34, v90, v34
	v_add_f32_e32 v34, v91, v34
	v_add_f32_e32 v34, v92, v34
	v_add_f32_e32 v34, v93, v34
	v_add_f32_e32 v34, v94, v34
	v_add_f32_e32 v34, v95, v34
	v_add_f32_e32 v34, v96, v34
	v_add_f32_e32 v34, v97, v34
	v_add_f32_e32 v147, v147, v34
	v_pk_mul_f32 v[2:3], v[2:3], v[250:251] op_sel_hi:[1,0]
	v_pk_mul_f32 v[4:5], v[4:5], v[250:251] op_sel_hi:[1,0]
	v_pk_mul_f32 v[6:7], v[6:7], v[250:251] op_sel_hi:[1,0]
	v_pk_mul_f32 v[8:9], v[8:9], v[250:251] op_sel_hi:[1,0]
	v_pk_mul_f32 v[10:11], v[10:11], v[250:251] op_sel_hi:[1,0]
	v_pk_mul_f32 v[12:13], v[12:13], v[250:251] op_sel_hi:[1,0]
	v_pk_mul_f32 v[14:15], v[14:15], v[250:251] op_sel_hi:[1,0]
	v_pk_mul_f32 v[16:17], v[16:17], v[250:251] op_sel_hi:[1,0]
	v_pk_mul_f32 v[18:19], v[18:19], v[250:251] op_sel_hi:[1,0]
	v_pk_mul_f32 v[20:21], v[20:21], v[250:251] op_sel_hi:[1,0]
	v_pk_mul_f32 v[22:23], v[22:23], v[250:251] op_sel_hi:[1,0]
	v_pk_mul_f32 v[24:25], v[24:25], v[250:251] op_sel_hi:[1,0]
	v_pk_mul_f32 v[26:27], v[26:27], v[250:251] op_sel_hi:[1,0]
	v_pk_mul_f32 v[28:29], v[28:29], v[250:251] op_sel_hi:[1,0]
	v_pk_mul_f32 v[30:31], v[30:31], v[250:251] op_sel_hi:[1,0]
	v_pk_mul_f32 v[32:33], v[32:33], v[250:251] op_sel_hi:[1,0]
	v_mul_f32_e32 v147, v147, v250

; #define GSYNC() do { xcd_barrier(xbar); if (REPS(30) > 1) xcd_barrier(xbar); } while (0)
; __device__ __forceinline__ void xcd_barrier(const XcdBarrier& b) {
;     asm volatile("s_waitcnt vmcnt(0)" ::: "memory");
;     __syncthreads();
;     if (threadIdx.x == 0) {
;         unsigned* bar = b.bar;
;         __builtin_amdgcn_s_waitcnt(0);
;         unsigned nloc = b.st[0], nx = b.st[1];
; __global__ void __launch_bounds__(NTHR, 2) mega_fwd(Params P) {
;     ...
;         GSYNC();
.LBB0_927:
	s_setprio 0
	s_waitcnt vmcnt(0)
	s_waitcnt lgkmcnt(0)
	s_barrier
	s_mov_b64 s[34:35], exec
	v_readlane_b32 s4, v248, 6
	v_readlane_b32 s5, v248, 7
	s_and_b64 s[4:5], s[34:35], s[4:5]
	s_mov_b64 exec, s[4:5]
	s_cbranch_execz .LBB0_979
	v_readlane_b32 s4, v247, 18
	s_waitcnt vmcnt(0) expcnt(0) lgkmcnt(0)
	s_nop 0
	v_mov_b32_e32 v1, s4
	ds_read_b32 v3, v1
	v_readlane_b32 s4, v247, 19
	s_waitcnt lgkmcnt(0)
	v_cmp_ne_u32_e32 vcc, 0, v3
	v_mov_b32_e32 v1, s4
	ds_read_b32 v2, v1
	s_cbranch_vccnz .LBB0_943
	s_mov_b32 s4, 1
	s_branch .LBB0_931

; __global__ void __launch_bounds__(NTHR, 2) mega_fwd(Params P) {
	.amdhsa_kernel _Z8mega_fwd6Params
		.amdhsa_group_segment_fixed_size 0
		.amdhsa_private_segment_fixed_size 0
		.amdhsa_kernarg_size 472
		.amdhsa_user_sgpr_count 2
		.amdhsa_user_sgpr_dispatch_ptr 0
		.amdhsa_user_sgpr_queue_ptr 0
		.amdhsa_user_sgpr_kernarg_segment_ptr 1
		.amdhsa_user_sgpr_dispatch_id 0
		.amdhsa_user_sgpr_kernarg_preload_length 0
		.amdhsa_user_sgpr_kernarg_preload_offset 0
		.amdhsa_user_sgpr_private_segment_size 0
		.amdhsa_uses_dynamic_stack 0
		.amdhsa_enable_private_segment 0
		.amdhsa_system_sgpr_workgroup_id_x 1
		.amdhsa_system_sgpr_workgroup_id_y 0
		.amdhsa_system_sgpr_workgroup_id_z 0
		.amdhsa_system_sgpr_workgroup_info 0
		.amdhsa_system_vgpr_workitem_id 2
		.amdhsa_next_free_vgpr 256
		.amdhsa_next_free_sgpr 102
		.amdhsa_accum_offset 256
		.amdhsa_reserve_vcc 1
		.amdhsa_float_round_mode_32 0
		.amdhsa_float_round_mode_16_64 0
		.amdhsa_float_denorm_mode_32 3
		.amdhsa_float_denorm_mode_16_64 3
		.amdhsa_dx10_clamp 1
		.amdhsa_ieee_mode 1
		.amdhsa_fp16_overflow 0
		.amdhsa_tg_split 0
		.amdhsa_exception_fp_ieee_invalid_op 0
		.amdhsa_exception_fp_denorm_src 0
		.amdhsa_exception_fp_ieee_div_zero 0
		.amdhsa_exception_fp_ieee_overflow 0
		.amdhsa_exception_fp_ieee_underflow 0
		.amdhsa_exception_fp_ieee_inexact 0
		.amdhsa_exception_int_div_zero 0
	.end_amdhsa_kernel

; __global__ void __launch_bounds__(NTHR, 2) mega_fwd(Params P) {
amdhsa.kernels:
  - .agpr_count:     0
    .args:
      - .offset:         0
        .size:           216
        .value_kind:     by_value
      - .offset:         216
        .size:           4
        .value_kind:     hidden_block_count_x
      - .offset:         220
        .size:           4
        .value_kind:     hidden_block_count_y
      - .offset:         224
        .size:           4
        .value_kind:     hidden_block_count_z
      - .offset:         228
        .size:           2
        .value_kind:     hidden_group_size_x
      - .offset:         230
        .size:           2
        .value_kind:     hidden_group_size_y
      - .offset:         232
        .size:           2
        .value_kind:     hidden_group_size_z
      - .offset:         234
        .size:           2
        .value_kind:     hidden_remainder_x
      - .offset:         236
        .size:           2
        .value_kind:     hidden_remainder_y
      - .offset:         238
        .size:           2
        .value_kind:     hidden_remainder_z
      - .offset:         256
        .size:           8
        .value_kind:     hidden_global_offset_x
      - .offset:         264
        .size:           8
        .value_kind:     hidden_global_offset_y
      - .offset:         272
        .size:           8
        .value_kind:     hidden_global_offset_z
      - .offset:         280
        .size:           2
        .value_kind:     hidden_grid_dims
      - .offset:         304
        .size:           8
        .value_kind:     hidden_multigrid_sync_arg
      - .offset:         336
        .size:           4
        .value_kind:     hidden_dynamic_lds_size
    .group_segment_fixed_size: 0
    .kernarg_segment_align: 8
    .kernarg_segment_size: 472
    .language:       OpenCL C
    .language_version:
      - 2
      - 0
    .max_flat_workgroup_size: 512
    .name:           _Z8mega_fwd6Params
    .private_segment_fixed_size: 0
    .sgpr_count:     108
    .sgpr_spill_count: 151
    .symbol:         _Z8mega_fwd6Params.kd
    .uniform_work_group_size: 1
    .uses_dynamic_stack: false
    .vgpr_count:     256
    .vgpr_spill_count: 0
    .wavefront_size: 64
